# grid barrier: globally last arriver releases every XCD generation word directly, per-XCD leaders no longer forward (on top of invalidate-at-arrival)
# speedup vs baseline: 1.0268x; 1.0020x over previous
.LBB0_9:
	s_or_b64 exec, exec, s[2:3]
	v_readlane_b32 s2, v252, 39
	v_readlane_b32 s3, v252, 40
	v_mov_b32_e32 v2, 1
	s_waitcnt vmcnt(0)
	s_nop 1
	s_nop 1
	s_waitcnt vmcnt(0)

.LBB0_778:
	s_or_b64 exec, exec, s[2:3]
	s_and_saveexec_b64 s[2:3], s[4:5]
	s_cbranch_execz .Ltramp_9
	v_mov_b32_e32 v2, 1
	global_atomic_add v[4:5], v2, off
	v_readlane_b32 s4, v252, 43
	s_nop 3
	v_cmp_eq_u32_e32 vcc, s4, v4
	s_nop 3
	s_cbranch_vccz .Ltramp_9
	v_readlane_b32 s4, v251, 1
	v_readlane_b32 s5, v251, 2
	s_nop 4
	s_add_u32 s4, s4, 0x2400
	s_addc_u32 s5, s5, 0
	global_atomic_add v3, v2, s[4:5]
	global_atomic_add v3, v2, s[4:5] offset:256
	global_atomic_add v3, v2, s[4:5] offset:512
	global_atomic_add v3, v2, s[4:5] offset:768
	global_atomic_add v3, v2, s[4:5] offset:1024
	global_atomic_add v3, v2, s[4:5] offset:1280
	global_atomic_add v3, v2, s[4:5] offset:1536
	global_atomic_add v3, v2, s[4:5] offset:1792
	global_atomic_add v3, v2, s[4:5] offset:2048
	global_atomic_add v3, v2, s[4:5] offset:2304
	global_atomic_add v3, v2, s[4:5] offset:2560
	global_atomic_add v3, v2, s[4:5] offset:2816
	global_atomic_add v3, v2, s[4:5] offset:3072
	global_atomic_add v3, v2, s[4:5] offset:3328
	global_atomic_add v3, v2, s[4:5] offset:3584
	global_atomic_add v3, v2, s[4:5] offset:3840
	s_branch .Ltramp_9
